# hand-written XCD grid barrier at 11 of 12 sites: global-last leader releases every XCD's XGEN word directly (one release hop), XCD leaders wait on their own XGEN word
# speedup vs baseline: 1.0033x; 1.0033x over previous
.LBB0_163:
	s_or_b64 exec, exec, s[2:3]
	s_cmp_eq_u32 s71, 2
	s_cbranch_scc1 .LBB0_226
	s_cmp_lg_u32 s70, 1
	s_mov_b64 s[2:3], -1
	s_cbranch_scc0 .LBB0_214
	s_waitcnt vmcnt(0)
	s_barrier
	s_mov_b64 s[2:3], exec
	v_readlane_b32 s4, v253, 6
	v_readlane_b32 s5, v253, 7
	s_and_b64 s[4:5], s[2:3], s[4:5]
	s_mov_b64 exec, s[4:5]
	s_cbranch_execz .LBB0_213
	v_readlane_b32 s98, v253, 2
	v_readlane_b32 s99, v253, 3
	v_mov_b32_e32 v1, 0x12000
	s_waitcnt vmcnt(0) expcnt(0) lgkmcnt(0)
	s_load_dwordx2 s[98:99], s[98:99], 0xf8
	ds_read_b128 v[4:7], v1
	s_getreg_b32 s100, hwreg(HW_REG_XCC_ID, 0, 4)
	s_and_b32 s100, s100, 15
	s_lshl_b32 s100, s100, 8
	s_add_u32 s100, s100, 0x38e00000
	s_waitcnt lgkmcnt(0)
	s_add_u32 s100, s98, s100
	s_addc_u32 s101, s99, 0
	v_mov_b32_e32 v2, 1
	v_mov_b32_e32 v3, 0x1400
	global_atomic_add v8, v3, v2, s[100:101] sc0
	s_waitcnt lgkmcnt(0)
	v_cvt_f32_u32_e32 v12, v4
	v_rcp_iflag_f32_e32 v12, v12
	v_sub_u32_e32 v13, 0, v4
	s_nop 1
	v_mul_f32_e32 v12, 0x4f7ffffe, v12
	v_cvt_u32_f32_e32 v12, v12
	v_mul_lo_u32 v13, v13, v12
	v_mul_hi_u32 v13, v12, v13
	v_add_u32_e32 v12, v12, v13
	s_waitcnt vmcnt(0)
	v_mul_hi_u32 v12, v8, v12
	v_mul_lo_u32 v13, v12, v4
	v_sub_u32_e32 v14, v8, v13
	v_add_u32_e32 v15, 1, v12
	v_cmp_ge_u32_e32 vcc, v14, v4
	v_sub_u32_e32 v13, v14, v4
	s_nop 1
	v_cndmask_b32_e32 v12, v12, v15, vcc
	v_cndmask_b32_e32 v14, v14, v13, vcc
	v_add_u32_e32 v15, 1, v12
	v_cmp_ge_u32_e32 vcc, v14, v4
	s_nop 1
	v_cndmask_b32_e32 v6, v12, v15, vcc
	v_add_u32_e32 v9, 1, v6
	v_mul_lo_u32 v10, v9, v4
	v_mul_lo_u32 v11, v9, v5
	v_add_u32_e32 v8, 1, v8
	v_cmp_ne_u32_e32 vcc, v8, v10
	s_cbranch_vccnz .Lxb_spin_1
	buffer_wbl2 sc1
	s_waitcnt vmcnt(0) lgkmcnt(0)
	v_mov_b32_e32 v3, 0x38e03400
	global_atomic_add v8, v3, v2, s[98:99] sc0
	s_waitcnt vmcnt(0)
	v_add_u32_e32 v8, 1, v8
	v_cmp_ne_u32_e32 vcc, v8, v11
	s_cbranch_vccnz .Lxb_spin_1
	v_mov_b32_e32 v3, 0x38e03500
	global_atomic_add v3, v2, s[98:99]
	v_mov_b32_e32 v12, 0x38e02400
	global_atomic_add v12, v2, s[98:99]
	v_mov_b32_e32 v13, 0x38e02500
	global_atomic_add v13, v2, s[98:99]
	v_mov_b32_e32 v14, 0x38e02600
	global_atomic_add v14, v2, s[98:99]
	v_mov_b32_e32 v15, 0x38e02700
	global_atomic_add v15, v2, s[98:99]
	v_mov_b32_e32 v12, 0x38e02800
	global_atomic_add v12, v2, s[98:99]
	v_mov_b32_e32 v13, 0x38e02900
	global_atomic_add v13, v2, s[98:99]
	v_mov_b32_e32 v14, 0x38e02a00
	global_atomic_add v14, v2, s[98:99]
	v_mov_b32_e32 v15, 0x38e02b00
	global_atomic_add v15, v2, s[98:99]
	v_mov_b32_e32 v12, 0x38e02c00
	global_atomic_add v12, v2, s[98:99]
	v_mov_b32_e32 v13, 0x38e02d00
	global_atomic_add v13, v2, s[98:99]
	v_mov_b32_e32 v14, 0x38e02e00
	global_atomic_add v14, v2, s[98:99]
	v_mov_b32_e32 v15, 0x38e02f00
	global_atomic_add v15, v2, s[98:99]
	v_mov_b32_e32 v12, 0x38e03000
	global_atomic_add v12, v2, s[98:99]
	v_mov_b32_e32 v13, 0x38e03100
	global_atomic_add v13, v2, s[98:99]
	v_mov_b32_e32 v14, 0x38e03200
	global_atomic_add v14, v2, s[98:99]
	v_mov_b32_e32 v15, 0x38e03300
	global_atomic_add v15, v2, s[98:99]
	s_branch .Lxb_acq_1
.Lxb_spin_1:
	v_mov_b32_e32 v3, 0x2400
	v_mov_b32_e32 v16, 0
.Lxb_poll_1:
	global_load_dword v8, v3, s[100:101] sc1
	s_waitcnt vmcnt(0)
	v_cmp_ne_u32_e32 vcc, v8, v6
	s_cbranch_vccnz .Lxb_acq_1
	s_sleep 1
	v_add_u32_e32 v16, 1, v16
	v_cmp_gt_u32_e32 vcc, 0x4000, v16
	s_cbranch_vccnz .Lxb_poll_1
.Lxb_acq_1:
	buffer_inv sc1
.Lxb_done_1:
	s_waitcnt vmcnt(0)
.LBB0_213:
	s_or_b64 exec, exec, s[2:3]
	s_mov_b64 s[2:3], 0
	s_waitcnt lgkmcnt(0)
	s_barrier

.LBB0_271:
	s_add_i32 s2, s30, 1
	s_cmp_ge_i32 s2, s71
	s_cbranch_scc1 .LBB0_284
	s_cmp_lg_u32 s30, s70
	s_mov_b64 s[44:45], -1
	s_cbranch_scc0 .LBB0_323
	s_waitcnt vmcnt(0)
	s_barrier
	s_mov_b64 s[44:45], exec
	v_readlane_b32 s38, v253, 6
	v_readlane_b32 s39, v253, 7
	s_and_b64 s[38:39], s[44:45], s[38:39]
	s_mov_b64 exec, s[38:39]
	s_cbranch_execz .LBB0_322
	v_readlane_b32 s98, v253, 2
	v_readlane_b32 s99, v253, 3
	v_mov_b32_e32 v1, 0x12000
	s_waitcnt vmcnt(0) expcnt(0) lgkmcnt(0)
	s_load_dwordx2 s[98:99], s[98:99], 0xf8
	ds_read_b128 v[4:7], v1
	s_getreg_b32 s100, hwreg(HW_REG_XCC_ID, 0, 4)
	s_and_b32 s100, s100, 15
	s_lshl_b32 s100, s100, 8
	s_add_u32 s100, s100, 0x38e00000
	s_waitcnt lgkmcnt(0)
	s_add_u32 s100, s98, s100
	s_addc_u32 s101, s99, 0
	v_mov_b32_e32 v2, 1
	v_mov_b32_e32 v3, 0x1400
	global_atomic_add v8, v3, v2, s[100:101] sc0
	s_waitcnt lgkmcnt(0)
	v_cvt_f32_u32_e32 v12, v4
	v_rcp_iflag_f32_e32 v12, v12
	v_sub_u32_e32 v13, 0, v4
	s_nop 1
	v_mul_f32_e32 v12, 0x4f7ffffe, v12
	v_cvt_u32_f32_e32 v12, v12
	v_mul_lo_u32 v13, v13, v12
	v_mul_hi_u32 v13, v12, v13
	v_add_u32_e32 v12, v12, v13
	s_waitcnt vmcnt(0)
	v_mul_hi_u32 v12, v8, v12
	v_mul_lo_u32 v13, v12, v4
	v_sub_u32_e32 v14, v8, v13
	v_add_u32_e32 v15, 1, v12
	v_cmp_ge_u32_e32 vcc, v14, v4
	v_sub_u32_e32 v13, v14, v4
	s_nop 1
	v_cndmask_b32_e32 v12, v12, v15, vcc
	v_cndmask_b32_e32 v14, v14, v13, vcc
	v_add_u32_e32 v15, 1, v12
	v_cmp_ge_u32_e32 vcc, v14, v4
	s_nop 1
	v_cndmask_b32_e32 v6, v12, v15, vcc
	v_add_u32_e32 v9, 1, v6
	v_mul_lo_u32 v10, v9, v4
	v_mul_lo_u32 v11, v9, v5
	v_add_u32_e32 v8, 1, v8
	v_cmp_ne_u32_e32 vcc, v8, v10
	s_cbranch_vccnz .Lxb_spin_2
	buffer_wbl2 sc1
	s_waitcnt vmcnt(0) lgkmcnt(0)
	v_mov_b32_e32 v3, 0x38e03400
	global_atomic_add v8, v3, v2, s[98:99] sc0
	s_waitcnt vmcnt(0)
	v_add_u32_e32 v8, 1, v8
	v_cmp_ne_u32_e32 vcc, v8, v11
	s_cbranch_vccnz .Lxb_spin_2
	v_mov_b32_e32 v3, 0x38e03500
	global_atomic_add v3, v2, s[98:99]
	v_mov_b32_e32 v12, 0x38e02400
	global_atomic_add v12, v2, s[98:99]
	v_mov_b32_e32 v13, 0x38e02500
	global_atomic_add v13, v2, s[98:99]
	v_mov_b32_e32 v14, 0x38e02600
	global_atomic_add v14, v2, s[98:99]
	v_mov_b32_e32 v15, 0x38e02700
	global_atomic_add v15, v2, s[98:99]
	v_mov_b32_e32 v12, 0x38e02800
	global_atomic_add v12, v2, s[98:99]
	v_mov_b32_e32 v13, 0x38e02900
	global_atomic_add v13, v2, s[98:99]
	v_mov_b32_e32 v14, 0x38e02a00
	global_atomic_add v14, v2, s[98:99]
	v_mov_b32_e32 v15, 0x38e02b00
	global_atomic_add v15, v2, s[98:99]
	v_mov_b32_e32 v12, 0x38e02c00
	global_atomic_add v12, v2, s[98:99]
	v_mov_b32_e32 v13, 0x38e02d00
	global_atomic_add v13, v2, s[98:99]
	v_mov_b32_e32 v14, 0x38e02e00
	global_atomic_add v14, v2, s[98:99]
	v_mov_b32_e32 v15, 0x38e02f00
	global_atomic_add v15, v2, s[98:99]
	v_mov_b32_e32 v12, 0x38e03000
	global_atomic_add v12, v2, s[98:99]
	v_mov_b32_e32 v13, 0x38e03100
	global_atomic_add v13, v2, s[98:99]
	v_mov_b32_e32 v14, 0x38e03200
	global_atomic_add v14, v2, s[98:99]
	v_mov_b32_e32 v15, 0x38e03300
	global_atomic_add v15, v2, s[98:99]
	s_branch .Lxb_acq_2

.Lxb_acq_2:
	buffer_inv sc1
.Lxb_done_2:
	s_waitcnt vmcnt(0)
.LBB0_322:
	s_or_b64 exec, exec, s[44:45]
	s_waitcnt lgkmcnt(0)
	s_barrier
	s_mov_b64 s[44:45], 0

.LBB0_384:
	s_add_i32 s31, s30, 2
	s_cmp_ge_i32 s31, s71
	s_cbranch_scc1 .LBB0_447
	s_cmp_lg_u32 s2, s70
	s_mov_b64 s[44:45], -1
	s_cbranch_scc0 .LBB0_435
	s_waitcnt vmcnt(0)
	s_barrier
	s_mov_b64 s[44:45], exec
	v_readlane_b32 s2, v253, 6
	v_readlane_b32 s3, v253, 7
	s_and_b64 s[2:3], s[44:45], s[2:3]
	s_mov_b64 exec, s[2:3]
	s_cbranch_execz .LBB0_434
	v_readlane_b32 s98, v253, 2
	v_readlane_b32 s99, v253, 3
	v_mov_b32_e32 v1, 0x12000
	s_waitcnt vmcnt(0) expcnt(0) lgkmcnt(0)
	s_load_dwordx2 s[98:99], s[98:99], 0xf8
	ds_read_b128 v[4:7], v1
	s_getreg_b32 s100, hwreg(HW_REG_XCC_ID, 0, 4)
	s_and_b32 s100, s100, 15
	s_lshl_b32 s100, s100, 8
	s_add_u32 s100, s100, 0x38e00000
	s_waitcnt lgkmcnt(0)
	s_add_u32 s100, s98, s100
	s_addc_u32 s101, s99, 0
	v_mov_b32_e32 v2, 1
	v_mov_b32_e32 v3, 0x1400
	global_atomic_add v8, v3, v2, s[100:101] sc0
	s_waitcnt lgkmcnt(0)
	v_cvt_f32_u32_e32 v12, v4
	v_rcp_iflag_f32_e32 v12, v12
	v_sub_u32_e32 v13, 0, v4
	s_nop 1
	v_mul_f32_e32 v12, 0x4f7ffffe, v12
	v_cvt_u32_f32_e32 v12, v12
	v_mul_lo_u32 v13, v13, v12
	v_mul_hi_u32 v13, v12, v13
	v_add_u32_e32 v12, v12, v13
	s_waitcnt vmcnt(0)
	v_mul_hi_u32 v12, v8, v12
	v_mul_lo_u32 v13, v12, v4
	v_sub_u32_e32 v14, v8, v13
	v_add_u32_e32 v15, 1, v12
	v_cmp_ge_u32_e32 vcc, v14, v4
	v_sub_u32_e32 v13, v14, v4
	s_nop 1
	v_cndmask_b32_e32 v12, v12, v15, vcc
	v_cndmask_b32_e32 v14, v14, v13, vcc
	v_add_u32_e32 v15, 1, v12
	v_cmp_ge_u32_e32 vcc, v14, v4
	s_nop 1
	v_cndmask_b32_e32 v6, v12, v15, vcc
	v_add_u32_e32 v9, 1, v6
	v_mul_lo_u32 v10, v9, v4
	v_mul_lo_u32 v11, v9, v5
	v_add_u32_e32 v8, 1, v8
	v_cmp_ne_u32_e32 vcc, v8, v10
	s_cbranch_vccnz .Lxb_spin_3
	buffer_wbl2 sc1
	s_waitcnt vmcnt(0) lgkmcnt(0)
	v_mov_b32_e32 v3, 0x38e03400
	global_atomic_add v8, v3, v2, s[98:99] sc0
	s_waitcnt vmcnt(0)
	v_add_u32_e32 v8, 1, v8
	v_cmp_ne_u32_e32 vcc, v8, v11
	s_cbranch_vccnz .Lxb_spin_3
	v_mov_b32_e32 v3, 0x38e03500
	global_atomic_add v3, v2, s[98:99]
	v_mov_b32_e32 v12, 0x38e02400
	global_atomic_add v12, v2, s[98:99]
	v_mov_b32_e32 v13, 0x38e02500
	global_atomic_add v13, v2, s[98:99]
	v_mov_b32_e32 v14, 0x38e02600
	global_atomic_add v14, v2, s[98:99]
	v_mov_b32_e32 v15, 0x38e02700
	global_atomic_add v15, v2, s[98:99]
	v_mov_b32_e32 v12, 0x38e02800
	global_atomic_add v12, v2, s[98:99]
	v_mov_b32_e32 v13, 0x38e02900
	global_atomic_add v13, v2, s[98:99]
	v_mov_b32_e32 v14, 0x38e02a00
	global_atomic_add v14, v2, s[98:99]
	v_mov_b32_e32 v15, 0x38e02b00
	global_atomic_add v15, v2, s[98:99]
	v_mov_b32_e32 v12, 0x38e02c00
	global_atomic_add v12, v2, s[98:99]
	v_mov_b32_e32 v13, 0x38e02d00
	global_atomic_add v13, v2, s[98:99]
	v_mov_b32_e32 v14, 0x38e02e00
	global_atomic_add v14, v2, s[98:99]
	v_mov_b32_e32 v15, 0x38e02f00
	global_atomic_add v15, v2, s[98:99]
	v_mov_b32_e32 v12, 0x38e03000
	global_atomic_add v12, v2, s[98:99]
	v_mov_b32_e32 v13, 0x38e03100
	global_atomic_add v13, v2, s[98:99]
	v_mov_b32_e32 v14, 0x38e03200
	global_atomic_add v14, v2, s[98:99]
	v_mov_b32_e32 v15, 0x38e03300
	global_atomic_add v15, v2, s[98:99]
	s_branch .Lxb_acq_3

.Lxb_acq_3:
	buffer_inv sc1
.Lxb_done_3:
	s_waitcnt vmcnt(0)
.LBB0_434:
	s_or_b64 exec, exec, s[44:45]
	s_mov_b64 s[44:45], 0
	s_waitcnt lgkmcnt(0)
	s_barrier

.LBB0_459:
	s_add_i32 s31, s30, 1
	s_cmp_ge_i32 s31, s71
	s_cbranch_scc1 .LBB0_522
	s_cmp_lg_u32 s30, s70
	s_mov_b64 s[42:43], -1
	s_cbranch_scc0 .LBB0_510
	s_waitcnt vmcnt(0)
	s_barrier
	s_mov_b64 s[42:43], exec
	v_readlane_b32 s2, v253, 6
	v_readlane_b32 s3, v253, 7
	s_and_b64 s[2:3], s[42:43], s[2:3]
	s_mov_b64 exec, s[2:3]
	s_cbranch_execz .LBB0_509
	v_readlane_b32 s98, v253, 2
	v_readlane_b32 s99, v253, 3
	v_mov_b32_e32 v1, 0x12000
	s_waitcnt vmcnt(0) expcnt(0) lgkmcnt(0)
	s_load_dwordx2 s[98:99], s[98:99], 0xf8
	ds_read_b128 v[4:7], v1
	s_getreg_b32 s100, hwreg(HW_REG_XCC_ID, 0, 4)
	s_and_b32 s100, s100, 15
	s_lshl_b32 s100, s100, 8
	s_add_u32 s100, s100, 0x38e00000
	s_waitcnt lgkmcnt(0)
	s_add_u32 s100, s98, s100
	s_addc_u32 s101, s99, 0
	v_mov_b32_e32 v2, 1
	v_mov_b32_e32 v3, 0x1400
	global_atomic_add v8, v3, v2, s[100:101] sc0
	s_waitcnt lgkmcnt(0)
	v_cvt_f32_u32_e32 v12, v4
	v_rcp_iflag_f32_e32 v12, v12
	v_sub_u32_e32 v13, 0, v4
	s_nop 1
	v_mul_f32_e32 v12, 0x4f7ffffe, v12
	v_cvt_u32_f32_e32 v12, v12
	v_mul_lo_u32 v13, v13, v12
	v_mul_hi_u32 v13, v12, v13
	v_add_u32_e32 v12, v12, v13
	s_waitcnt vmcnt(0)
	v_mul_hi_u32 v12, v8, v12
	v_mul_lo_u32 v13, v12, v4
	v_sub_u32_e32 v14, v8, v13
	v_add_u32_e32 v15, 1, v12
	v_cmp_ge_u32_e32 vcc, v14, v4
	v_sub_u32_e32 v13, v14, v4
	s_nop 1
	v_cndmask_b32_e32 v12, v12, v15, vcc
	v_cndmask_b32_e32 v14, v14, v13, vcc
	v_add_u32_e32 v15, 1, v12
	v_cmp_ge_u32_e32 vcc, v14, v4
	s_nop 1
	v_cndmask_b32_e32 v6, v12, v15, vcc
	v_add_u32_e32 v9, 1, v6
	v_mul_lo_u32 v10, v9, v4
	v_mul_lo_u32 v11, v9, v5
	v_add_u32_e32 v8, 1, v8
	v_cmp_ne_u32_e32 vcc, v8, v10
	s_cbranch_vccnz .Lxb_spin_4
	buffer_wbl2 sc1
	s_waitcnt vmcnt(0) lgkmcnt(0)
	v_mov_b32_e32 v3, 0x38e03400
	global_atomic_add v8, v3, v2, s[98:99] sc0
	s_waitcnt vmcnt(0)
	v_add_u32_e32 v8, 1, v8
	v_cmp_ne_u32_e32 vcc, v8, v11
	s_cbranch_vccnz .Lxb_spin_4
	v_mov_b32_e32 v3, 0x38e03500
	global_atomic_add v3, v2, s[98:99]
	v_mov_b32_e32 v12, 0x38e02400
	global_atomic_add v12, v2, s[98:99]
	v_mov_b32_e32 v13, 0x38e02500
	global_atomic_add v13, v2, s[98:99]
	v_mov_b32_e32 v14, 0x38e02600
	global_atomic_add v14, v2, s[98:99]
	v_mov_b32_e32 v15, 0x38e02700
	global_atomic_add v15, v2, s[98:99]
	v_mov_b32_e32 v12, 0x38e02800
	global_atomic_add v12, v2, s[98:99]
	v_mov_b32_e32 v13, 0x38e02900
	global_atomic_add v13, v2, s[98:99]
	v_mov_b32_e32 v14, 0x38e02a00
	global_atomic_add v14, v2, s[98:99]
	v_mov_b32_e32 v15, 0x38e02b00
	global_atomic_add v15, v2, s[98:99]
	v_mov_b32_e32 v12, 0x38e02c00
	global_atomic_add v12, v2, s[98:99]
	v_mov_b32_e32 v13, 0x38e02d00
	global_atomic_add v13, v2, s[98:99]
	v_mov_b32_e32 v14, 0x38e02e00
	global_atomic_add v14, v2, s[98:99]
	v_mov_b32_e32 v15, 0x38e02f00
	global_atomic_add v15, v2, s[98:99]
	v_mov_b32_e32 v12, 0x38e03000
	global_atomic_add v12, v2, s[98:99]
	v_mov_b32_e32 v13, 0x38e03100
	global_atomic_add v13, v2, s[98:99]
	v_mov_b32_e32 v14, 0x38e03200
	global_atomic_add v14, v2, s[98:99]
	v_mov_b32_e32 v15, 0x38e03300
	global_atomic_add v15, v2, s[98:99]
	s_branch .Lxb_acq_4

.Lxb_acq_4:
	buffer_inv sc1
.Lxb_done_4:
	s_waitcnt vmcnt(0)
.LBB0_509:
	s_or_b64 exec, exec, s[42:43]
	s_mov_b64 s[42:43], 0
	s_waitcnt lgkmcnt(0)
	s_barrier

.LBB0_641:
	s_add_i32 s3, s30, 2
	s_cmp_ge_i32 s3, s71
	s_cbranch_scc1 .LBB0_704
	s_cmp_lg_u32 s31, s70
	s_mov_b64 s[42:43], -1
	s_cbranch_scc0 .LBB0_692
	s_waitcnt vmcnt(0)
	s_waitcnt lgkmcnt(0)
	s_barrier
	s_mov_b64 s[42:43], exec
	v_readlane_b32 s38, v253, 6
	v_readlane_b32 s39, v253, 7
	s_and_b64 s[38:39], s[42:43], s[38:39]
	s_mov_b64 exec, s[38:39]
	s_cbranch_execz .LBB0_691
	v_readlane_b32 s98, v253, 2
	v_readlane_b32 s99, v253, 3
	v_mov_b32_e32 v1, 0x12000
	s_waitcnt vmcnt(0) expcnt(0) lgkmcnt(0)
	s_load_dwordx2 s[98:99], s[98:99], 0xf8
	ds_read_b128 v[4:7], v1
	s_getreg_b32 s100, hwreg(HW_REG_XCC_ID, 0, 4)
	s_and_b32 s100, s100, 15
	s_lshl_b32 s100, s100, 8
	s_add_u32 s100, s100, 0x38e00000
	s_waitcnt lgkmcnt(0)
	s_add_u32 s100, s98, s100
	s_addc_u32 s101, s99, 0
	v_mov_b32_e32 v2, 1
	v_mov_b32_e32 v3, 0x1400
	global_atomic_add v8, v3, v2, s[100:101] sc0
	s_waitcnt lgkmcnt(0)
	v_cvt_f32_u32_e32 v12, v4
	v_rcp_iflag_f32_e32 v12, v12
	v_sub_u32_e32 v13, 0, v4
	s_nop 1
	v_mul_f32_e32 v12, 0x4f7ffffe, v12
	v_cvt_u32_f32_e32 v12, v12
	v_mul_lo_u32 v13, v13, v12
	v_mul_hi_u32 v13, v12, v13
	v_add_u32_e32 v12, v12, v13
	s_waitcnt vmcnt(0)
	v_mul_hi_u32 v12, v8, v12
	v_mul_lo_u32 v13, v12, v4
	v_sub_u32_e32 v14, v8, v13
	v_add_u32_e32 v15, 1, v12
	v_cmp_ge_u32_e32 vcc, v14, v4
	v_sub_u32_e32 v13, v14, v4
	s_nop 1
	v_cndmask_b32_e32 v12, v12, v15, vcc
	v_cndmask_b32_e32 v14, v14, v13, vcc
	v_add_u32_e32 v15, 1, v12
	v_cmp_ge_u32_e32 vcc, v14, v4
	s_nop 1
	v_cndmask_b32_e32 v6, v12, v15, vcc
	v_add_u32_e32 v9, 1, v6
	v_mul_lo_u32 v10, v9, v4
	v_mul_lo_u32 v11, v9, v5
	v_add_u32_e32 v8, 1, v8
	v_cmp_ne_u32_e32 vcc, v8, v10
	s_cbranch_vccnz .Lxb_spin_5
	buffer_wbl2 sc1
	s_waitcnt vmcnt(0) lgkmcnt(0)
	v_mov_b32_e32 v3, 0x38e03400
	global_atomic_add v8, v3, v2, s[98:99] sc0
	s_waitcnt vmcnt(0)
	v_add_u32_e32 v8, 1, v8
	v_cmp_ne_u32_e32 vcc, v8, v11
	s_cbranch_vccnz .Lxb_spin_5
	v_mov_b32_e32 v3, 0x38e03500
	global_atomic_add v3, v2, s[98:99]
	v_mov_b32_e32 v12, 0x38e02400
	global_atomic_add v12, v2, s[98:99]
	v_mov_b32_e32 v13, 0x38e02500
	global_atomic_add v13, v2, s[98:99]
	v_mov_b32_e32 v14, 0x38e02600
	global_atomic_add v14, v2, s[98:99]
	v_mov_b32_e32 v15, 0x38e02700
	global_atomic_add v15, v2, s[98:99]
	v_mov_b32_e32 v12, 0x38e02800
	global_atomic_add v12, v2, s[98:99]
	v_mov_b32_e32 v13, 0x38e02900
	global_atomic_add v13, v2, s[98:99]
	v_mov_b32_e32 v14, 0x38e02a00
	global_atomic_add v14, v2, s[98:99]
	v_mov_b32_e32 v15, 0x38e02b00
	global_atomic_add v15, v2, s[98:99]
	v_mov_b32_e32 v12, 0x38e02c00
	global_atomic_add v12, v2, s[98:99]
	v_mov_b32_e32 v13, 0x38e02d00
	global_atomic_add v13, v2, s[98:99]
	v_mov_b32_e32 v14, 0x38e02e00
	global_atomic_add v14, v2, s[98:99]
	v_mov_b32_e32 v15, 0x38e02f00
	global_atomic_add v15, v2, s[98:99]
	v_mov_b32_e32 v12, 0x38e03000
	global_atomic_add v12, v2, s[98:99]
	v_mov_b32_e32 v13, 0x38e03100
	global_atomic_add v13, v2, s[98:99]
	v_mov_b32_e32 v14, 0x38e03200
	global_atomic_add v14, v2, s[98:99]
	v_mov_b32_e32 v15, 0x38e03300
	global_atomic_add v15, v2, s[98:99]
	s_branch .Lxb_acq_5

.Lxb_acq_5:
	buffer_inv sc1
.Lxb_done_5:
	s_waitcnt vmcnt(0)
.LBB0_691:
	s_or_b64 exec, exec, s[42:43]
	s_mov_b64 s[42:43], 0
	s_waitcnt lgkmcnt(0)
	s_barrier

.LBB0_714:
	s_or_b64 exec, exec, s[44:45]
	s_add_i32 s2, s30, 3
	s_cmp_ge_i32 s2, s71
	s_cbranch_scc1 .LBB0_777
	s_cmp_lg_u32 s3, s70
	s_mov_b64 s[42:43], -1
	s_cbranch_scc0 .LBB0_765
	s_waitcnt vmcnt(0)
	s_waitcnt lgkmcnt(0)
	s_barrier
	s_mov_b64 s[42:43], exec
	v_readlane_b32 s38, v253, 6
	v_readlane_b32 s39, v253, 7
	s_and_b64 s[38:39], s[42:43], s[38:39]
	s_mov_b64 exec, s[38:39]
	s_cbranch_execz .LBB0_764
	v_readlane_b32 s98, v253, 2
	v_readlane_b32 s99, v253, 3
	v_mov_b32_e32 v1, 0x12000
	s_waitcnt vmcnt(0) expcnt(0) lgkmcnt(0)
	s_load_dwordx2 s[98:99], s[98:99], 0xf8
	ds_read_b128 v[4:7], v1
	s_getreg_b32 s100, hwreg(HW_REG_XCC_ID, 0, 4)
	s_and_b32 s100, s100, 15
	s_lshl_b32 s100, s100, 8
	s_add_u32 s100, s100, 0x38e00000
	s_waitcnt lgkmcnt(0)
	s_add_u32 s100, s98, s100
	s_addc_u32 s101, s99, 0
	v_mov_b32_e32 v2, 1
	v_mov_b32_e32 v3, 0x1400
	global_atomic_add v8, v3, v2, s[100:101] sc0
	s_waitcnt lgkmcnt(0)
	v_cvt_f32_u32_e32 v12, v4
	v_rcp_iflag_f32_e32 v12, v12
	v_sub_u32_e32 v13, 0, v4
	s_nop 1
	v_mul_f32_e32 v12, 0x4f7ffffe, v12
	v_cvt_u32_f32_e32 v12, v12
	v_mul_lo_u32 v13, v13, v12
	v_mul_hi_u32 v13, v12, v13
	v_add_u32_e32 v12, v12, v13
	s_waitcnt vmcnt(0)
	v_mul_hi_u32 v12, v8, v12
	v_mul_lo_u32 v13, v12, v4
	v_sub_u32_e32 v14, v8, v13
	v_add_u32_e32 v15, 1, v12
	v_cmp_ge_u32_e32 vcc, v14, v4
	v_sub_u32_e32 v13, v14, v4
	s_nop 1
	v_cndmask_b32_e32 v12, v12, v15, vcc
	v_cndmask_b32_e32 v14, v14, v13, vcc
	v_add_u32_e32 v15, 1, v12
	v_cmp_ge_u32_e32 vcc, v14, v4
	s_nop 1
	v_cndmask_b32_e32 v6, v12, v15, vcc
	v_add_u32_e32 v9, 1, v6
	v_mul_lo_u32 v10, v9, v4
	v_mul_lo_u32 v11, v9, v5
	v_add_u32_e32 v8, 1, v8
	v_cmp_ne_u32_e32 vcc, v8, v10
	s_cbranch_vccnz .Lxb_spin_6
	buffer_wbl2 sc1
	s_waitcnt vmcnt(0) lgkmcnt(0)
	v_mov_b32_e32 v3, 0x38e03400
	global_atomic_add v8, v3, v2, s[98:99] sc0
	s_waitcnt vmcnt(0)
	v_add_u32_e32 v8, 1, v8
	v_cmp_ne_u32_e32 vcc, v8, v11
	s_cbranch_vccnz .Lxb_spin_6
	v_mov_b32_e32 v3, 0x38e03500
	global_atomic_add v3, v2, s[98:99]
	v_mov_b32_e32 v12, 0x38e02400
	global_atomic_add v12, v2, s[98:99]
	v_mov_b32_e32 v13, 0x38e02500
	global_atomic_add v13, v2, s[98:99]
	v_mov_b32_e32 v14, 0x38e02600
	global_atomic_add v14, v2, s[98:99]
	v_mov_b32_e32 v15, 0x38e02700
	global_atomic_add v15, v2, s[98:99]
	v_mov_b32_e32 v12, 0x38e02800
	global_atomic_add v12, v2, s[98:99]
	v_mov_b32_e32 v13, 0x38e02900
	global_atomic_add v13, v2, s[98:99]
	v_mov_b32_e32 v14, 0x38e02a00
	global_atomic_add v14, v2, s[98:99]
	v_mov_b32_e32 v15, 0x38e02b00
	global_atomic_add v15, v2, s[98:99]
	v_mov_b32_e32 v12, 0x38e02c00
	global_atomic_add v12, v2, s[98:99]
	v_mov_b32_e32 v13, 0x38e02d00
	global_atomic_add v13, v2, s[98:99]
	v_mov_b32_e32 v14, 0x38e02e00
	global_atomic_add v14, v2, s[98:99]
	v_mov_b32_e32 v15, 0x38e02f00
	global_atomic_add v15, v2, s[98:99]
	v_mov_b32_e32 v12, 0x38e03000
	global_atomic_add v12, v2, s[98:99]
	v_mov_b32_e32 v13, 0x38e03100
	global_atomic_add v13, v2, s[98:99]
	v_mov_b32_e32 v14, 0x38e03200
	global_atomic_add v14, v2, s[98:99]
	v_mov_b32_e32 v15, 0x38e03300
	global_atomic_add v15, v2, s[98:99]
	s_branch .Lxb_acq_6

.Lxb_acq_6:
	buffer_inv sc1
.Lxb_done_6:
	s_waitcnt vmcnt(0)
.LBB0_764:
	s_or_b64 exec, exec, s[42:43]
	s_mov_b64 s[42:43], 0
	s_waitcnt lgkmcnt(0)
	s_barrier

.LBB0_789:
	s_add_i32 s31, s30, 4
	s_cmp_ge_i32 s31, s71
	s_cbranch_scc1 .LBB0_852
	s_cmp_lg_u32 s2, s70
	s_mov_b64 s[42:43], -1
	s_cbranch_scc0 .LBB0_840
	s_waitcnt vmcnt(0)
	s_waitcnt lgkmcnt(0)
	s_barrier
	s_mov_b64 s[42:43], exec
	v_readlane_b32 s2, v253, 6
	v_readlane_b32 s3, v253, 7
	s_and_b64 s[2:3], s[42:43], s[2:3]
	s_mov_b64 exec, s[2:3]
	s_cbranch_execz .LBB0_839
	v_readlane_b32 s98, v253, 2
	v_readlane_b32 s99, v253, 3
	v_mov_b32_e32 v1, 0x12000
	s_waitcnt vmcnt(0) expcnt(0) lgkmcnt(0)
	s_load_dwordx2 s[98:99], s[98:99], 0xf8
	ds_read_b128 v[4:7], v1
	s_getreg_b32 s100, hwreg(HW_REG_XCC_ID, 0, 4)
	s_and_b32 s100, s100, 15
	s_lshl_b32 s100, s100, 8
	s_add_u32 s100, s100, 0x38e00000
	s_waitcnt lgkmcnt(0)
	s_add_u32 s100, s98, s100
	s_addc_u32 s101, s99, 0
	v_mov_b32_e32 v2, 1
	v_mov_b32_e32 v3, 0x1400
	global_atomic_add v8, v3, v2, s[100:101] sc0
	s_waitcnt lgkmcnt(0)
	v_cvt_f32_u32_e32 v12, v4
	v_rcp_iflag_f32_e32 v12, v12
	v_sub_u32_e32 v13, 0, v4
	s_nop 1
	v_mul_f32_e32 v12, 0x4f7ffffe, v12
	v_cvt_u32_f32_e32 v12, v12
	v_mul_lo_u32 v13, v13, v12
	v_mul_hi_u32 v13, v12, v13
	v_add_u32_e32 v12, v12, v13
	s_waitcnt vmcnt(0)
	v_mul_hi_u32 v12, v8, v12
	v_mul_lo_u32 v13, v12, v4
	v_sub_u32_e32 v14, v8, v13
	v_add_u32_e32 v15, 1, v12
	v_cmp_ge_u32_e32 vcc, v14, v4
	v_sub_u32_e32 v13, v14, v4
	s_nop 1
	v_cndmask_b32_e32 v12, v12, v15, vcc
	v_cndmask_b32_e32 v14, v14, v13, vcc
	v_add_u32_e32 v15, 1, v12
	v_cmp_ge_u32_e32 vcc, v14, v4
	s_nop 1
	v_cndmask_b32_e32 v6, v12, v15, vcc
	v_add_u32_e32 v9, 1, v6
	v_mul_lo_u32 v10, v9, v4
	v_mul_lo_u32 v11, v9, v5
	v_add_u32_e32 v8, 1, v8
	v_cmp_ne_u32_e32 vcc, v8, v10
	s_cbranch_vccnz .Lxb_spin_7
	buffer_wbl2 sc1
	s_waitcnt vmcnt(0) lgkmcnt(0)
	v_mov_b32_e32 v3, 0x38e03400
	global_atomic_add v8, v3, v2, s[98:99] sc0
	s_waitcnt vmcnt(0)
	v_add_u32_e32 v8, 1, v8
	v_cmp_ne_u32_e32 vcc, v8, v11
	s_cbranch_vccnz .Lxb_spin_7
	v_mov_b32_e32 v3, 0x38e03500
	global_atomic_add v3, v2, s[98:99]
	v_mov_b32_e32 v12, 0x38e02400
	global_atomic_add v12, v2, s[98:99]
	v_mov_b32_e32 v13, 0x38e02500
	global_atomic_add v13, v2, s[98:99]
	v_mov_b32_e32 v14, 0x38e02600
	global_atomic_add v14, v2, s[98:99]
	v_mov_b32_e32 v15, 0x38e02700
	global_atomic_add v15, v2, s[98:99]
	v_mov_b32_e32 v12, 0x38e02800
	global_atomic_add v12, v2, s[98:99]
	v_mov_b32_e32 v13, 0x38e02900
	global_atomic_add v13, v2, s[98:99]
	v_mov_b32_e32 v14, 0x38e02a00
	global_atomic_add v14, v2, s[98:99]
	v_mov_b32_e32 v15, 0x38e02b00
	global_atomic_add v15, v2, s[98:99]
	v_mov_b32_e32 v12, 0x38e02c00
	global_atomic_add v12, v2, s[98:99]
	v_mov_b32_e32 v13, 0x38e02d00
	global_atomic_add v13, v2, s[98:99]
	v_mov_b32_e32 v14, 0x38e02e00
	global_atomic_add v14, v2, s[98:99]
	v_mov_b32_e32 v15, 0x38e02f00
	global_atomic_add v15, v2, s[98:99]
	v_mov_b32_e32 v12, 0x38e03000
	global_atomic_add v12, v2, s[98:99]
	v_mov_b32_e32 v13, 0x38e03100
	global_atomic_add v13, v2, s[98:99]
	v_mov_b32_e32 v14, 0x38e03200
	global_atomic_add v14, v2, s[98:99]
	v_mov_b32_e32 v15, 0x38e03300
	global_atomic_add v15, v2, s[98:99]
	s_branch .Lxb_acq_7

.Lxb_acq_7:
	buffer_inv sc1
.Lxb_done_7:
	s_waitcnt vmcnt(0)
.LBB0_839:
	s_or_b64 exec, exec, s[42:43]
	s_mov_b64 s[42:43], 0
	s_waitcnt lgkmcnt(0)
	s_barrier

.LBB0_862:
	s_add_i32 s2, s31, 1
	s_cmp_ge_i32 s2, s71
	s_cbranch_scc1 .LBB0_925
	s_cmp_lg_u32 s31, s70
	s_mov_b64 s[44:45], -1
	s_cbranch_scc0 .LBB0_913
	s_waitcnt vmcnt(0)
	s_waitcnt lgkmcnt(0)
	s_barrier
	s_mov_b64 s[44:45], exec
	v_readlane_b32 s38, v253, 6
	v_readlane_b32 s39, v253, 7
	s_and_b64 s[38:39], s[44:45], s[38:39]
	s_mov_b64 exec, s[38:39]
	s_cbranch_execz .LBB0_912
	v_readlane_b32 s98, v253, 2
	v_readlane_b32 s99, v253, 3
	v_mov_b32_e32 v1, 0x12000
	s_waitcnt vmcnt(0) expcnt(0) lgkmcnt(0)
	s_load_dwordx2 s[98:99], s[98:99], 0xf8
	ds_read_b128 v[4:7], v1
	s_getreg_b32 s100, hwreg(HW_REG_XCC_ID, 0, 4)
	s_and_b32 s100, s100, 15
	s_lshl_b32 s100, s100, 8
	s_add_u32 s100, s100, 0x38e00000
	s_waitcnt lgkmcnt(0)
	s_add_u32 s100, s98, s100
	s_addc_u32 s101, s99, 0
	v_mov_b32_e32 v2, 1
	v_mov_b32_e32 v3, 0x1400
	global_atomic_add v8, v3, v2, s[100:101] sc0
	s_waitcnt lgkmcnt(0)
	v_cvt_f32_u32_e32 v12, v4
	v_rcp_iflag_f32_e32 v12, v12
	v_sub_u32_e32 v13, 0, v4
	s_nop 1
	v_mul_f32_e32 v12, 0x4f7ffffe, v12
	v_cvt_u32_f32_e32 v12, v12
	v_mul_lo_u32 v13, v13, v12
	v_mul_hi_u32 v13, v12, v13
	v_add_u32_e32 v12, v12, v13
	s_waitcnt vmcnt(0)
	v_mul_hi_u32 v12, v8, v12
	v_mul_lo_u32 v13, v12, v4
	v_sub_u32_e32 v14, v8, v13
	v_add_u32_e32 v15, 1, v12
	v_cmp_ge_u32_e32 vcc, v14, v4
	v_sub_u32_e32 v13, v14, v4
	s_nop 1
	v_cndmask_b32_e32 v12, v12, v15, vcc
	v_cndmask_b32_e32 v14, v14, v13, vcc
	v_add_u32_e32 v15, 1, v12
	v_cmp_ge_u32_e32 vcc, v14, v4
	s_nop 1
	v_cndmask_b32_e32 v6, v12, v15, vcc
	v_add_u32_e32 v9, 1, v6
	v_mul_lo_u32 v10, v9, v4
	v_mul_lo_u32 v11, v9, v5
	v_add_u32_e32 v8, 1, v8
	v_cmp_ne_u32_e32 vcc, v8, v10
	s_cbranch_vccnz .Lxb_spin_8
	buffer_wbl2 sc1
	s_waitcnt vmcnt(0) lgkmcnt(0)
	v_mov_b32_e32 v3, 0x38e03400
	global_atomic_add v8, v3, v2, s[98:99] sc0
	s_waitcnt vmcnt(0)
	v_add_u32_e32 v8, 1, v8
	v_cmp_ne_u32_e32 vcc, v8, v11
	s_cbranch_vccnz .Lxb_spin_8
	v_mov_b32_e32 v3, 0x38e03500
	global_atomic_add v3, v2, s[98:99]
	v_mov_b32_e32 v12, 0x38e02400
	global_atomic_add v12, v2, s[98:99]
	v_mov_b32_e32 v13, 0x38e02500
	global_atomic_add v13, v2, s[98:99]
	v_mov_b32_e32 v14, 0x38e02600
	global_atomic_add v14, v2, s[98:99]
	v_mov_b32_e32 v15, 0x38e02700
	global_atomic_add v15, v2, s[98:99]
	v_mov_b32_e32 v12, 0x38e02800
	global_atomic_add v12, v2, s[98:99]
	v_mov_b32_e32 v13, 0x38e02900
	global_atomic_add v13, v2, s[98:99]
	v_mov_b32_e32 v14, 0x38e02a00
	global_atomic_add v14, v2, s[98:99]
	v_mov_b32_e32 v15, 0x38e02b00
	global_atomic_add v15, v2, s[98:99]
	v_mov_b32_e32 v12, 0x38e02c00
	global_atomic_add v12, v2, s[98:99]
	v_mov_b32_e32 v13, 0x38e02d00
	global_atomic_add v13, v2, s[98:99]
	v_mov_b32_e32 v14, 0x38e02e00
	global_atomic_add v14, v2, s[98:99]
	v_mov_b32_e32 v15, 0x38e02f00
	global_atomic_add v15, v2, s[98:99]
	v_mov_b32_e32 v12, 0x38e03000
	global_atomic_add v12, v2, s[98:99]
	v_mov_b32_e32 v13, 0x38e03100
	global_atomic_add v13, v2, s[98:99]
	v_mov_b32_e32 v14, 0x38e03200
	global_atomic_add v14, v2, s[98:99]
	v_mov_b32_e32 v15, 0x38e03300
	global_atomic_add v15, v2, s[98:99]
	s_branch .Lxb_acq_8

.Lxb_acq_8:
	buffer_inv sc1
.Lxb_done_8:
	s_waitcnt vmcnt(0)
.LBB0_912:
	s_or_b64 exec, exec, s[44:45]
	s_mov_b64 s[44:45], 0
	s_waitcnt lgkmcnt(0)
	s_barrier

.LBB0_933:
	s_or_b64 exec, exec, s[46:47]
	s_add_i32 s30, s31, 2
	s_cmp_ge_i32 s30, s71
	s_cbranch_scc1 .LBB0_996
	s_cmp_lg_u32 s2, s70
	s_mov_b64 s[44:45], -1
	s_cbranch_scc0 .LBB0_984
	s_waitcnt vmcnt(0)
	s_waitcnt lgkmcnt(0)
	s_barrier
	s_mov_b64 s[44:45], exec
	v_readlane_b32 s2, v253, 6
	v_readlane_b32 s3, v253, 7
	s_and_b64 s[2:3], s[44:45], s[2:3]
	s_mov_b64 exec, s[2:3]
	s_cbranch_execz .LBB0_983
	v_readlane_b32 s98, v253, 2
	v_readlane_b32 s99, v253, 3
	v_mov_b32_e32 v1, 0x12000
	s_waitcnt vmcnt(0) expcnt(0) lgkmcnt(0)
	s_load_dwordx2 s[98:99], s[98:99], 0xf8
	ds_read_b128 v[4:7], v1
	s_getreg_b32 s100, hwreg(HW_REG_XCC_ID, 0, 4)
	s_and_b32 s100, s100, 15
	s_lshl_b32 s100, s100, 8
	s_add_u32 s100, s100, 0x38e00000
	s_waitcnt lgkmcnt(0)
	s_add_u32 s100, s98, s100
	s_addc_u32 s101, s99, 0
	v_mov_b32_e32 v2, 1
	v_mov_b32_e32 v3, 0x1400
	global_atomic_add v8, v3, v2, s[100:101] sc0
	s_waitcnt lgkmcnt(0)
	v_cvt_f32_u32_e32 v12, v4
	v_rcp_iflag_f32_e32 v12, v12
	v_sub_u32_e32 v13, 0, v4
	s_nop 1
	v_mul_f32_e32 v12, 0x4f7ffffe, v12
	v_cvt_u32_f32_e32 v12, v12
	v_mul_lo_u32 v13, v13, v12
	v_mul_hi_u32 v13, v12, v13
	v_add_u32_e32 v12, v12, v13
	s_waitcnt vmcnt(0)
	v_mul_hi_u32 v12, v8, v12
	v_mul_lo_u32 v13, v12, v4
	v_sub_u32_e32 v14, v8, v13
	v_add_u32_e32 v15, 1, v12
	v_cmp_ge_u32_e32 vcc, v14, v4
	v_sub_u32_e32 v13, v14, v4
	s_nop 1
	v_cndmask_b32_e32 v12, v12, v15, vcc
	v_cndmask_b32_e32 v14, v14, v13, vcc
	v_add_u32_e32 v15, 1, v12
	v_cmp_ge_u32_e32 vcc, v14, v4
	s_nop 1
	v_cndmask_b32_e32 v6, v12, v15, vcc
	v_add_u32_e32 v9, 1, v6
	v_mul_lo_u32 v10, v9, v4
	v_mul_lo_u32 v11, v9, v5
	v_add_u32_e32 v8, 1, v8
	v_cmp_ne_u32_e32 vcc, v8, v10
	s_cbranch_vccnz .Lxb_spin_9
	buffer_wbl2 sc1
	s_waitcnt vmcnt(0) lgkmcnt(0)
	v_mov_b32_e32 v3, 0x38e03400
	global_atomic_add v8, v3, v2, s[98:99] sc0
	s_waitcnt vmcnt(0)
	v_add_u32_e32 v8, 1, v8
	v_cmp_ne_u32_e32 vcc, v8, v11
	s_cbranch_vccnz .Lxb_spin_9
	v_mov_b32_e32 v3, 0x38e03500
	global_atomic_add v3, v2, s[98:99]
	v_mov_b32_e32 v12, 0x38e02400
	global_atomic_add v12, v2, s[98:99]
	v_mov_b32_e32 v13, 0x38e02500
	global_atomic_add v13, v2, s[98:99]
	v_mov_b32_e32 v14, 0x38e02600
	global_atomic_add v14, v2, s[98:99]
	v_mov_b32_e32 v15, 0x38e02700
	global_atomic_add v15, v2, s[98:99]
	v_mov_b32_e32 v12, 0x38e02800
	global_atomic_add v12, v2, s[98:99]
	v_mov_b32_e32 v13, 0x38e02900
	global_atomic_add v13, v2, s[98:99]
	v_mov_b32_e32 v14, 0x38e02a00
	global_atomic_add v14, v2, s[98:99]
	v_mov_b32_e32 v15, 0x38e02b00
	global_atomic_add v15, v2, s[98:99]
	v_mov_b32_e32 v12, 0x38e02c00
	global_atomic_add v12, v2, s[98:99]
	v_mov_b32_e32 v13, 0x38e02d00
	global_atomic_add v13, v2, s[98:99]
	v_mov_b32_e32 v14, 0x38e02e00
	global_atomic_add v14, v2, s[98:99]
	v_mov_b32_e32 v15, 0x38e02f00
	global_atomic_add v15, v2, s[98:99]
	v_mov_b32_e32 v12, 0x38e03000
	global_atomic_add v12, v2, s[98:99]
	v_mov_b32_e32 v13, 0x38e03100
	global_atomic_add v13, v2, s[98:99]
	v_mov_b32_e32 v14, 0x38e03200
	global_atomic_add v14, v2, s[98:99]
	v_mov_b32_e32 v15, 0x38e03300
	global_atomic_add v15, v2, s[98:99]
	s_branch .Lxb_acq_9

.Lxb_acq_9:
	buffer_inv sc1
.Lxb_done_9:
	s_waitcnt vmcnt(0)
.LBB0_983:
	s_or_b64 exec, exec, s[44:45]
	s_mov_b64 s[44:45], 0
	s_waitcnt lgkmcnt(0)
	s_barrier

.LBB0_1007:
	s_add_i32 s92, s31, 3
	s_cmp_ge_i32 s92, s71
	s_cbranch_scc1 .LBB0_1070
	s_cmp_lg_u32 s30, s70
	s_mov_b64 s[42:43], -1
	s_cbranch_scc0 .LBB0_1058
	s_waitcnt vmcnt(0)
	s_waitcnt lgkmcnt(0)
	s_barrier
	s_mov_b64 s[42:43], exec
	v_readlane_b32 s2, v253, 6
	v_readlane_b32 s3, v253, 7
	s_and_b64 s[2:3], s[42:43], s[2:3]
	s_mov_b64 exec, s[2:3]
	s_cbranch_execz .LBB0_1057
	v_readlane_b32 s98, v253, 2
	v_readlane_b32 s99, v253, 3
	v_mov_b32_e32 v1, 0x12000
	s_waitcnt vmcnt(0) expcnt(0) lgkmcnt(0)
	s_load_dwordx2 s[98:99], s[98:99], 0xf8
	ds_read_b128 v[4:7], v1
	s_getreg_b32 s100, hwreg(HW_REG_XCC_ID, 0, 4)
	s_and_b32 s100, s100, 15
	s_lshl_b32 s100, s100, 8
	s_add_u32 s100, s100, 0x38e00000
	s_waitcnt lgkmcnt(0)
	s_add_u32 s100, s98, s100
	s_addc_u32 s101, s99, 0
	v_mov_b32_e32 v2, 1
	v_mov_b32_e32 v3, 0x1400
	global_atomic_add v8, v3, v2, s[100:101] sc0
	s_waitcnt lgkmcnt(0)
	v_cvt_f32_u32_e32 v12, v4
	v_rcp_iflag_f32_e32 v12, v12
	v_sub_u32_e32 v13, 0, v4
	s_nop 1
	v_mul_f32_e32 v12, 0x4f7ffffe, v12
	v_cvt_u32_f32_e32 v12, v12
	v_mul_lo_u32 v13, v13, v12
	v_mul_hi_u32 v13, v12, v13
	v_add_u32_e32 v12, v12, v13
	s_waitcnt vmcnt(0)
	v_mul_hi_u32 v12, v8, v12
	v_mul_lo_u32 v13, v12, v4
	v_sub_u32_e32 v14, v8, v13
	v_add_u32_e32 v15, 1, v12
	v_cmp_ge_u32_e32 vcc, v14, v4
	v_sub_u32_e32 v13, v14, v4
	s_nop 1
	v_cndmask_b32_e32 v12, v12, v15, vcc
	v_cndmask_b32_e32 v14, v14, v13, vcc
	v_add_u32_e32 v15, 1, v12
	v_cmp_ge_u32_e32 vcc, v14, v4
	s_nop 1
	v_cndmask_b32_e32 v6, v12, v15, vcc
	v_add_u32_e32 v9, 1, v6
	v_mul_lo_u32 v10, v9, v4
	v_mul_lo_u32 v11, v9, v5
	v_add_u32_e32 v8, 1, v8
	v_cmp_ne_u32_e32 vcc, v8, v10
	s_cbranch_vccnz .Lxb_spin_10
	buffer_wbl2 sc1
	s_waitcnt vmcnt(0) lgkmcnt(0)
	v_mov_b32_e32 v3, 0x38e03400
	global_atomic_add v8, v3, v2, s[98:99] sc0
	s_waitcnt vmcnt(0)
	v_add_u32_e32 v8, 1, v8
	v_cmp_ne_u32_e32 vcc, v8, v11
	s_cbranch_vccnz .Lxb_spin_10
	v_mov_b32_e32 v3, 0x38e03500
	global_atomic_add v3, v2, s[98:99]
	v_mov_b32_e32 v12, 0x38e02400
	global_atomic_add v12, v2, s[98:99]
	v_mov_b32_e32 v13, 0x38e02500
	global_atomic_add v13, v2, s[98:99]
	v_mov_b32_e32 v14, 0x38e02600
	global_atomic_add v14, v2, s[98:99]
	v_mov_b32_e32 v15, 0x38e02700
	global_atomic_add v15, v2, s[98:99]
	v_mov_b32_e32 v12, 0x38e02800
	global_atomic_add v12, v2, s[98:99]
	v_mov_b32_e32 v13, 0x38e02900
	global_atomic_add v13, v2, s[98:99]
	v_mov_b32_e32 v14, 0x38e02a00
	global_atomic_add v14, v2, s[98:99]
	v_mov_b32_e32 v15, 0x38e02b00
	global_atomic_add v15, v2, s[98:99]
	v_mov_b32_e32 v12, 0x38e02c00
	global_atomic_add v12, v2, s[98:99]
	v_mov_b32_e32 v13, 0x38e02d00
	global_atomic_add v13, v2, s[98:99]
	v_mov_b32_e32 v14, 0x38e02e00
	global_atomic_add v14, v2, s[98:99]
	v_mov_b32_e32 v15, 0x38e02f00
	global_atomic_add v15, v2, s[98:99]
	v_mov_b32_e32 v12, 0x38e03000
	global_atomic_add v12, v2, s[98:99]
	v_mov_b32_e32 v13, 0x38e03100
	global_atomic_add v13, v2, s[98:99]
	v_mov_b32_e32 v14, 0x38e03200
	global_atomic_add v14, v2, s[98:99]
	v_mov_b32_e32 v15, 0x38e03300
	global_atomic_add v15, v2, s[98:99]
	s_branch .Lxb_acq_10

.Lxb_acq_10:
	buffer_inv sc1
.Lxb_done_10:
	s_waitcnt vmcnt(0)
.LBB0_1057:
	s_or_b64 exec, exec, s[42:43]
	s_mov_b64 s[42:43], 0
	s_waitcnt lgkmcnt(0)
	s_barrier

.LBB0_1148:
	s_or_b64 exec, exec, s[46:47]
	s_add_i32 s30, s31, 4
	s_cmp_ge_i32 s30, s71
	s_cbranch_scc1 .LBB0_229
	s_cmp_lg_u32 s92, s70
	s_mov_b64 s[42:43], -1
	s_cbranch_scc0 .LBB0_1199
	s_waitcnt vmcnt(0)
	s_barrier
	s_mov_b64 s[42:43], exec
	v_readlane_b32 s2, v253, 6
	v_readlane_b32 s3, v253, 7
	s_and_b64 s[2:3], s[42:43], s[2:3]
	s_mov_b64 exec, s[2:3]
	s_cbranch_execz .LBB0_1198
	v_readlane_b32 s98, v253, 2
	v_readlane_b32 s99, v253, 3
	v_mov_b32_e32 v1, 0x12000
	s_waitcnt vmcnt(0) expcnt(0) lgkmcnt(0)
	s_load_dwordx2 s[98:99], s[98:99], 0xf8
	ds_read_b128 v[4:7], v1
	s_getreg_b32 s100, hwreg(HW_REG_XCC_ID, 0, 4)
	s_and_b32 s100, s100, 15
	s_lshl_b32 s100, s100, 8
	s_add_u32 s100, s100, 0x38e00000
	s_waitcnt lgkmcnt(0)
	s_add_u32 s100, s98, s100
	s_addc_u32 s101, s99, 0
	v_mov_b32_e32 v2, 1
	v_mov_b32_e32 v3, 0x1400
	global_atomic_add v8, v3, v2, s[100:101] sc0
	s_waitcnt lgkmcnt(0)
	v_cvt_f32_u32_e32 v12, v4
	v_rcp_iflag_f32_e32 v12, v12
	v_sub_u32_e32 v13, 0, v4
	s_nop 1
	v_mul_f32_e32 v12, 0x4f7ffffe, v12
	v_cvt_u32_f32_e32 v12, v12
	v_mul_lo_u32 v13, v13, v12
	v_mul_hi_u32 v13, v12, v13
	v_add_u32_e32 v12, v12, v13
	s_waitcnt vmcnt(0)
	v_mul_hi_u32 v12, v8, v12
	v_mul_lo_u32 v13, v12, v4
	v_sub_u32_e32 v14, v8, v13
	v_add_u32_e32 v15, 1, v12
	v_cmp_ge_u32_e32 vcc, v14, v4
	v_sub_u32_e32 v13, v14, v4
	s_nop 1
	v_cndmask_b32_e32 v12, v12, v15, vcc
	v_cndmask_b32_e32 v14, v14, v13, vcc
	v_add_u32_e32 v15, 1, v12
	v_cmp_ge_u32_e32 vcc, v14, v4
	s_nop 1
	v_cndmask_b32_e32 v6, v12, v15, vcc
	v_add_u32_e32 v9, 1, v6
	v_mul_lo_u32 v10, v9, v4
	v_mul_lo_u32 v11, v9, v5
	v_add_u32_e32 v8, 1, v8
	v_cmp_ne_u32_e32 vcc, v8, v10
	s_cbranch_vccnz .Lxb_spin_11
	buffer_wbl2 sc1
	s_waitcnt vmcnt(0) lgkmcnt(0)
	v_mov_b32_e32 v3, 0x38e03400
	global_atomic_add v8, v3, v2, s[98:99] sc0
	s_waitcnt vmcnt(0)
	v_add_u32_e32 v8, 1, v8
	v_cmp_ne_u32_e32 vcc, v8, v11
	s_cbranch_vccnz .Lxb_spin_11
	v_mov_b32_e32 v3, 0x38e03500
	global_atomic_add v3, v2, s[98:99]
	v_mov_b32_e32 v12, 0x38e02400
	global_atomic_add v12, v2, s[98:99]
	v_mov_b32_e32 v13, 0x38e02500
	global_atomic_add v13, v2, s[98:99]
	v_mov_b32_e32 v14, 0x38e02600
	global_atomic_add v14, v2, s[98:99]
	v_mov_b32_e32 v15, 0x38e02700
	global_atomic_add v15, v2, s[98:99]
	v_mov_b32_e32 v12, 0x38e02800
	global_atomic_add v12, v2, s[98:99]
	v_mov_b32_e32 v13, 0x38e02900
	global_atomic_add v13, v2, s[98:99]
	v_mov_b32_e32 v14, 0x38e02a00
	global_atomic_add v14, v2, s[98:99]
	v_mov_b32_e32 v15, 0x38e02b00
	global_atomic_add v15, v2, s[98:99]
	v_mov_b32_e32 v12, 0x38e02c00
	global_atomic_add v12, v2, s[98:99]
	v_mov_b32_e32 v13, 0x38e02d00
	global_atomic_add v13, v2, s[98:99]
	v_mov_b32_e32 v14, 0x38e02e00
	global_atomic_add v14, v2, s[98:99]
	v_mov_b32_e32 v15, 0x38e02f00
	global_atomic_add v15, v2, s[98:99]
	v_mov_b32_e32 v12, 0x38e03000
	global_atomic_add v12, v2, s[98:99]
	v_mov_b32_e32 v13, 0x38e03100
	global_atomic_add v13, v2, s[98:99]
	v_mov_b32_e32 v14, 0x38e03200
	global_atomic_add v14, v2, s[98:99]
	v_mov_b32_e32 v15, 0x38e03300
	global_atomic_add v15, v2, s[98:99]
	s_branch .Lxb_acq_11

.Lxb_acq_11:
	buffer_inv sc1
.Lxb_done_11:
	s_waitcnt vmcnt(0)
.LBB0_1198:
	s_or_b64 exec, exec, s[42:43]
	s_mov_b64 s[42:43], 0
	s_waitcnt lgkmcnt(0)
	s_barrier
